# SGU VT build: dead scalar load (bias pointer, superseded by the item-start prefetch) replaced by nops of the same size
# speedup vs baseline: 1.0042x; 1.0042x over previous
.LBB0_249:
	s_or_b64 exec, exec, s[8:9]
	v_lshl_add_u32 v50, v73, 1, 0
	s_movk_i32 s14, 0x110
	v_cvt_pk_bf16_f32 v22, v22, v23
	v_cvt_pk_bf16_f32 v23, v24, v25
	v_cvt_pk_bf16_f32 v24, v18, v19
	s_waitcnt lgkmcnt(1)
	v_mad_u64_u32 v[18:19], s[8:9], v74, s14, v[50:51]
	v_cvt_pk_bf16_f32 v25, v20, v21
	ds_write_b128 v18, v[22:25]
	v_mad_u64_u32 v[22:23], s[8:9], v71, s14, v[50:51]
	v_cvt_pk_bf16_f32 v18, v30, v31
	v_cvt_pk_bf16_f32 v19, v32, v33
	v_cvt_pk_bf16_f32 v20, v26, v27
	v_cvt_pk_bf16_f32 v21, v28, v29
	ds_write_b128 v22, v[18:21]
	v_mad_u64_u32 v[22:23], s[8:9], v70, s14, v[50:51]
	v_cvt_pk_bf16_f32 v18, v38, v39
	v_cvt_pk_bf16_f32 v19, v40, v41
	v_cvt_pk_bf16_f32 v20, v34, v35
	v_cvt_pk_bf16_f32 v21, v36, v37
	ds_write_b128 v22, v[18:21]
	v_mad_u64_u32 v[22:23], s[8:9], v69, s14, v[50:51]
	v_cvt_pk_bf16_f32 v18, v46, v47
	v_cvt_pk_bf16_f32 v19, v48, v49
	v_cvt_pk_bf16_f32 v20, v42, v43
	v_cvt_pk_bf16_f32 v21, v44, v45
	ds_write_b128 v22, v[18:21]
	s_waitcnt lgkmcnt(0)
	s_barrier
	v_readlane_b32 s16, v255, 38
	v_readlane_b32 s17, v255, 39
	s_lshl_b64 s[12:13], s[16:17], 2
	v_and_b32_e32 v26, 0xffff0000, v14
	s_waitcnt lgkmcnt(0)
	s_add_u32 s8, s8, s12
	s_addc_u32 s9, s9, s13
	s_lshl_b32 s12, s7, 2
	s_add_u32 s8, s8, s12
	s_addc_u32 s9, s9, 0
	v_and_b32_e32 v156, 15, v68
	v_bfe_u32 v157, v68, 4, 2
	v_and_b32_e32 v158, -16, v72
	v_lshl_or_b32 v158, v157, 2, v158
	v_ashrrev_i32_e32 v159, 31, v158
	v_mov_b32_e32 v160, s20
	v_mov_b32_e32 v161, 0
	v_lshl_add_u64 v[162:163], v[158:159], 1, v[160:161]
	s_add_i32 s98, s11, 16
	v_add_lshl_u32 v160, s98, v156, 11
	v_lshl_add_u64 v[164:165], v[162:163], 0, v[160:161]
	s_lshl_b32 s98, s10, 16
	s_and_b32 s98, s98, 0x3fc0000
	v_lshl_or_b32 v160, v156, 11, s98
	v_lshl_add_u64 v[162:163], v[162:163], 0, v[160:161]
	v_lshl_add_u64 v[164:165], s[64:65], 0, v[164:165]
	v_lshl_add_u64 v[162:163], s[64:65], 0, v[162:163]
	s_add_i32 s98, s16, s7
	v_add_u32_e32 v166, s98, v156
	v_ashrrev_i32_e32 v167, 31, v166
	v_lshl_add_u64 v[166:167], v[166:167], 2, s[100:101]
	global_load_dword v80, v[166:167], off
	global_load_dword v81, v[166:167], off offset:64
	global_load_dword v82, v[166:167], off offset:128
	global_load_dword v83, v[166:167], off offset:192
	global_load_dword v84, v[166:167], off offset:256
	global_load_dword v85, v[166:167], off offset:320
	global_load_dword v86, v[166:167], off offset:384
	global_load_dword v87, v[166:167], off offset:448
	s_mov_b32 s98, 0xc200000
	s_mov_b32 s99, 0
	v_lshl_add_u64 v[160:161], v[162:163], 0, s[98:99]
	global_load_dwordx2 v[88:89], v[160:161], off
	v_lshl_add_u64 v[160:161], v[164:165], 0, s[98:99]
	global_load_dwordx2 v[90:91], v[160:161], off
	s_add_u32 s98, s98, 0x10000
	v_lshl_add_u64 v[160:161], v[162:163], 0, s[98:99]
	global_load_dwordx2 v[92:93], v[160:161], off
	v_lshl_add_u64 v[160:161], v[164:165], 0, s[98:99]
	global_load_dwordx2 v[94:95], v[160:161], off
	s_add_u32 s98, s98, 0x10000
	v_lshl_add_u64 v[160:161], v[162:163], 0, s[98:99]
	global_load_dwordx2 v[96:97], v[160:161], off
	v_lshl_add_u64 v[160:161], v[164:165], 0, s[98:99]
	global_load_dwordx2 v[98:99], v[160:161], off
	s_add_u32 s98, s98, 0x10000
	v_lshl_add_u64 v[160:161], v[162:163], 0, s[98:99]
	global_load_dwordx2 v[100:101], v[160:161], off
	v_lshl_add_u64 v[160:161], v[164:165], 0, s[98:99]
	global_load_dwordx2 v[102:103], v[160:161], off
	s_nop 0
	s_nop 0
	s_add_i32 s12, 0, 0x20000
	v_lshlrev_b32_e32 v0, 16, v14
	v_lshl_add_u32 v14, v74, 2, s12
	v_lshlrev_b32_e32 v27, 16, v15
	v_and_b32_e32 v28, 0xffff0000, v15
	ds_read2st64_b32 v[14:15], v14 offset1:2
	v_lshlrev_b32_e32 v29, 16, v16
	v_and_b32_e32 v16, 0xffff0000, v16
	v_lshlrev_b32_e32 v30, 16, v17
	v_and_b32_e32 v17, 0xffff0000, v17
	s_waitcnt lgkmcnt(0)
	v_sub_f32_e32 v0, v0, v14
	v_sub_f32_e32 v26, v26, v14
	v_sub_f32_e32 v27, v27, v14
	v_sub_f32_e32 v28, v28, v14
	v_sub_f32_e32 v29, v29, v14
	v_sub_f32_e32 v16, v16, v14
	v_sub_f32_e32 v30, v30, v14
	v_sub_f32_e32 v14, v17, v14
	v_mul_f32_e32 v0, v15, v0
	v_mul_f32_e32 v17, v15, v26
	v_mul_f32_e32 v26, v15, v27
	v_mul_f32_e32 v27, v15, v28
	v_mul_f32_e32 v28, v15, v29
	v_mul_f32_e32 v16, v15, v16
	v_mul_f32_e32 v29, v15, v30
	v_mul_f32_e32 v14, v15, v14
	v_xor_b32_e32 v31, v74, v73
	v_lshlrev_b32_e32 v31, 1, v31
	v_mul_u32_u24_e32 v32, 0x110, v73
	v_add3_u32 v31, 0, v31, v32
	s_nop 0
	s_nop 0
	s_add_i32 s11, s11, 16
	s_lshl_b32 s6, s6, 7
	s_waitcnt vmcnt(17)
	v_mul_f32_e32 v0, v168, v0
	v_mul_f32_e32 v15, v169, v17
	v_mul_f32_e32 v17, v170, v26
	v_mul_f32_e32 v26, v171, v27
	s_waitcnt vmcnt(16)
	v_mul_f32_e32 v27, v172, v28
	v_mul_f32_e32 v16, v173, v16
	v_mul_f32_e32 v28, v174, v29
	v_mul_f32_e32 v29, v175, v14
	v_bfe_u32 v14, v0, 16, 1
	v_bfe_u32 v30, v15, 16, 1
	v_bfe_u32 v33, v17, 16, 1
	v_bfe_u32 v34, v26, 16, 1
	v_bfe_u32 v35, v27, 16, 1
	v_bfe_u32 v36, v16, 16, 1
	v_add3_u32 v0, v0, v14, s90
	v_add3_u32 v14, v15, v30, s90
	v_add3_u32 v15, v17, v33, s90
	v_add3_u32 v17, v26, v34, s90
	v_add3_u32 v26, v27, v35, s90
	v_add3_u32 v16, v16, v36, s90
	ds_write_b16_d16_hi v31, v0 offset:34816
	ds_write_b16_d16_hi v31, v14 offset:35088
	ds_write_b16_d16_hi v31, v15 offset:35360
	ds_write_b16_d16_hi v31, v17 offset:35632
	ds_write_b16_d16_hi v31, v26 offset:35904
	ds_write_b16_d16_hi v31, v16 offset:36176
	v_bfe_u32 v0, v28, 16, 1
	v_add3_u32 v0, v28, v0, s90
	ds_write_b16_d16_hi v31, v0 offset:36448
	v_lshl_add_u32 v0, v71, 2, s12
	ds_read2st64_b32 v[14:15], v0 offset1:2
	v_bfe_u32 v0, v29, 16, 1
	v_add3_u32 v0, v29, v0, s90
	ds_write_b16_d16_hi v31, v0 offset:36720
	v_lshlrev_b32_e32 v0, 16, v10
	s_waitcnt lgkmcnt(0)
	v_sub_f32_e32 v0, v0, v14
	v_mul_f32_e32 v0, v15, v0
	v_and_b32_e32 v10, 0xffff0000, v10
	v_lshlrev_b32_e32 v16, 16, v11
	v_and_b32_e32 v11, 0xffff0000, v11
	v_lshlrev_b32_e32 v17, 16, v12
	v_and_b32_e32 v12, 0xffff0000, v12
	v_lshlrev_b32_e32 v26, 16, v13
	v_and_b32_e32 v13, 0xffff0000, v13
	v_mul_f32_e32 v0, v168, v0
	v_sub_f32_e32 v10, v10, v14
	v_sub_f32_e32 v16, v16, v14
	v_sub_f32_e32 v11, v11, v14
	v_sub_f32_e32 v17, v17, v14
	v_sub_f32_e32 v12, v12, v14
	v_sub_f32_e32 v26, v26, v14
	v_sub_f32_e32 v13, v13, v14
	v_mul_f32_e32 v10, v15, v10
	v_mul_f32_e32 v16, v15, v16
	v_mul_f32_e32 v11, v15, v11
	v_mul_f32_e32 v17, v15, v17
	v_mul_f32_e32 v12, v15, v12
	v_mul_f32_e32 v26, v15, v26
	v_mul_f32_e32 v13, v15, v13
	v_xor_b32_e32 v14, v71, v73
	v_lshlrev_b32_e32 v14, 1, v14
	v_bfe_u32 v15, v0, 16, 1
	v_mul_f32_e32 v10, v169, v10
	v_add3_u32 v0, v0, v15, s90
	v_add3_u32 v14, 0, v14, v32
	ds_write_b16_d16_hi v14, v0 offset:34816
	v_bfe_u32 v0, v10, 16, 1
	v_mul_f32_e32 v16, v170, v16
	v_add3_u32 v0, v10, v0, s90
	ds_write_b16_d16_hi v14, v0 offset:35088
	v_bfe_u32 v0, v16, 16, 1
	v_mul_f32_e32 v11, v171, v11
	v_add3_u32 v0, v16, v0, s90
	ds_write_b16_d16_hi v14, v0 offset:35360
	v_bfe_u32 v0, v11, 16, 1
	v_mul_f32_e32 v17, v172, v17
	v_add3_u32 v0, v11, v0, s90
	ds_write_b16_d16_hi v14, v0 offset:35632
	v_bfe_u32 v0, v17, 16, 1
	v_mul_f32_e32 v12, v173, v12
	v_add3_u32 v0, v17, v0, s90
	ds_write_b16_d16_hi v14, v0 offset:35904
	v_bfe_u32 v0, v12, 16, 1
	v_mul_f32_e32 v26, v174, v26
	v_add3_u32 v0, v12, v0, s90
	ds_write_b16_d16_hi v14, v0 offset:36176
	v_bfe_u32 v0, v26, 16, 1
	v_add3_u32 v0, v26, v0, s90
	ds_write_b16_d16_hi v14, v0 offset:36448
	v_lshl_add_u32 v0, v70, 2, s12
	ds_read2st64_b32 v[10:11], v0 offset1:2
	v_mul_f32_e32 v13, v175, v13
	v_bfe_u32 v0, v13, 16, 1
	v_add3_u32 v0, v13, v0, s90
	ds_write_b16_d16_hi v14, v0 offset:36720
	v_lshlrev_b32_e32 v0, 16, v6
	s_waitcnt lgkmcnt(1)
	v_sub_f32_e32 v0, v0, v10
	v_mul_f32_e32 v0, v11, v0
	v_and_b32_e32 v6, 0xffff0000, v6
	v_lshlrev_b32_e32 v12, 16, v7
	v_and_b32_e32 v7, 0xffff0000, v7
	v_lshlrev_b32_e32 v13, 16, v8
	v_and_b32_e32 v8, 0xffff0000, v8
	v_lshlrev_b32_e32 v14, 16, v9
	v_and_b32_e32 v9, 0xffff0000, v9
	v_mul_f32_e32 v0, v168, v0
	v_sub_f32_e32 v6, v6, v10
	v_sub_f32_e32 v12, v12, v10
	v_sub_f32_e32 v7, v7, v10
	v_sub_f32_e32 v13, v13, v10
	v_sub_f32_e32 v8, v8, v10
	v_sub_f32_e32 v14, v14, v10
	v_sub_f32_e32 v9, v9, v10
	v_mul_f32_e32 v6, v11, v6
	v_mul_f32_e32 v12, v11, v12
	v_mul_f32_e32 v7, v11, v7
	v_mul_f32_e32 v13, v11, v13
	v_mul_f32_e32 v8, v11, v8
	v_mul_f32_e32 v14, v11, v14
	v_mul_f32_e32 v9, v11, v9
	v_xor_b32_e32 v10, v70, v73
	v_lshlrev_b32_e32 v10, 1, v10
	v_bfe_u32 v11, v0, 16, 1
	v_mul_f32_e32 v6, v169, v6
	v_add3_u32 v0, v0, v11, s90
	v_add3_u32 v10, 0, v10, v32
	ds_write_b16_d16_hi v10, v0 offset:34816
	v_bfe_u32 v0, v6, 16, 1
	v_mul_f32_e32 v12, v170, v12
	v_add3_u32 v0, v6, v0, s90
	ds_write_b16_d16_hi v10, v0 offset:35088
	v_bfe_u32 v0, v12, 16, 1
	v_mul_f32_e32 v7, v171, v7
	v_add3_u32 v0, v12, v0, s90
	ds_write_b16_d16_hi v10, v0 offset:35360
	v_bfe_u32 v0, v7, 16, 1
	v_mul_f32_e32 v13, v172, v13
	v_add3_u32 v0, v7, v0, s90
	ds_write_b16_d16_hi v10, v0 offset:35632
	v_bfe_u32 v0, v13, 16, 1
	v_mul_f32_e32 v8, v173, v8
	v_add3_u32 v0, v13, v0, s90
	ds_write_b16_d16_hi v10, v0 offset:35904
	v_bfe_u32 v0, v8, 16, 1
	v_mul_f32_e32 v14, v174, v14
	v_add3_u32 v0, v8, v0, s90
	ds_write_b16_d16_hi v10, v0 offset:36176
	v_bfe_u32 v0, v14, 16, 1
	v_add3_u32 v0, v14, v0, s90
	ds_write_b16_d16_hi v10, v0 offset:36448
	v_lshl_add_u32 v0, v69, 2, s12
	ds_read2st64_b32 v[6:7], v0 offset1:2
	v_mul_f32_e32 v9, v175, v9
	v_bfe_u32 v0, v9, 16, 1
	v_add3_u32 v0, v9, v0, s90
	ds_write_b16_d16_hi v10, v0 offset:36720
	v_lshlrev_b32_e32 v0, 16, v2
	s_waitcnt lgkmcnt(1)
	v_sub_f32_e32 v0, v0, v6
	v_mul_f32_e32 v0, v7, v0
	v_and_b32_e32 v2, 0xffff0000, v2
	v_lshlrev_b32_e32 v8, 16, v3
	v_and_b32_e32 v3, 0xffff0000, v3
	v_lshlrev_b32_e32 v9, 16, v4
	v_and_b32_e32 v4, 0xffff0000, v4
	v_lshlrev_b32_e32 v10, 16, v5
	v_and_b32_e32 v5, 0xffff0000, v5
	v_mul_f32_e32 v0, v168, v0
	v_sub_f32_e32 v2, v2, v6
	v_sub_f32_e32 v8, v8, v6
	v_sub_f32_e32 v3, v3, v6
	v_sub_f32_e32 v9, v9, v6
	v_sub_f32_e32 v4, v4, v6
	v_sub_f32_e32 v10, v10, v6
	v_sub_f32_e32 v5, v5, v6
	v_mul_f32_e32 v2, v7, v2
	v_mul_f32_e32 v8, v7, v8
	v_mul_f32_e32 v3, v7, v3
	v_mul_f32_e32 v9, v7, v9
	v_mul_f32_e32 v4, v7, v4
	v_mul_f32_e32 v10, v7, v10
	v_mul_f32_e32 v5, v7, v5
	v_xor_b32_e32 v6, v69, v73
	v_lshlrev_b32_e32 v6, 1, v6
	v_bfe_u32 v7, v0, 16, 1
	v_mul_f32_e32 v2, v169, v2
	v_add3_u32 v0, v0, v7, s90
	v_add3_u32 v6, 0, v6, v32
	ds_write_b16_d16_hi v6, v0 offset:34816
	v_bfe_u32 v0, v2, 16, 1
	v_mul_f32_e32 v8, v170, v8
	v_add3_u32 v0, v2, v0, s90
	ds_write_b16_d16_hi v6, v0 offset:35088
	v_bfe_u32 v0, v8, 16, 1
	v_mul_f32_e32 v3, v171, v3
	v_add3_u32 v0, v8, v0, s90
	ds_write_b16_d16_hi v6, v0 offset:35360
	v_bfe_u32 v0, v3, 16, 1
	v_mul_f32_e32 v9, v172, v9
	v_add3_u32 v0, v3, v0, s90
	ds_write_b16_d16_hi v6, v0 offset:35632
	v_bfe_u32 v0, v9, 16, 1
	v_mul_f32_e32 v4, v173, v4
	v_add3_u32 v0, v9, v0, s90
	ds_write_b16_d16_hi v6, v0 offset:35904
	v_bfe_u32 v0, v4, 16, 1
	v_mul_f32_e32 v10, v174, v10
	v_add3_u32 v0, v4, v0, s90
	ds_write_b16_d16_hi v6, v0 offset:36176
	v_bfe_u32 v0, v10, 16, 1
	v_mul_f32_e32 v5, v175, v5
	v_add3_u32 v0, v10, v0, s90
	ds_write_b16_d16_hi v6, v0 offset:36448
	v_bfe_u32 v0, v5, 16, 1
	v_add3_u32 v0, v5, v0, s90
	ds_write_b16_d16_hi v6, v0 offset:36720
	v_bfe_u32 v18, v68, 4, 2
	v_bfi_b32 v0, -16, v72, v68
	v_and_b32_e32 v200, 0x18, v0
	v_lshrrev_b32_e32 v201, 5, v0
	v_lshlrev_b32_e32 v200, 1, v200
	v_and_b32_e32 v201, 3, v201
	v_and_b32_e32 v19, -16, v72
	v_mul_lo_u32 v0, v0, s14
	v_lshlrev_b32_e32 v22, 4, v18
	v_lshlrev_b32_e32 v201, 6, v201
	v_xor_b32_e32 v200, v22, v200
	v_add3_u32 v0, 0, v0, v200
	v_xor_b32_e32 v203, 64, v201
	v_xor_b32_e32 v204, 0x80, v201
	v_xor_b32_e32 v205, 0xc0, v201
	v_add_u32_e32 v202, v0, v201
	v_add_u32_e32 v203, v0, v203
	v_add_u32_e32 v204, v0, v204
	v_add_u32_e32 v205, v0, v205
	v_lshl_or_b32 v18, v18, 2, v19
	s_waitcnt lgkmcnt(0)
	s_barrier
	v_and_b32_e32 v23, 15, v68
	ds_read_b128 v[2:5], v202 offset:34816
	ds_read_b128 v[6:9], v203 offset:34816
	ds_read_b128 v[10:13], v204 offset:34816
	ds_read_b128 v[14:17], v205 offset:34816
	v_mov_b32_e32 v0, s20
	v_ashrrev_i32_e32 v19, 31, v18
	v_lshl_add_u64 v[24:25], v[18:19], 1, v[0:1]
	v_add_lshl_u32 v0, s11, v23, 11
	s_ashr_i32 s12, s6, 31
	v_or_b32_e32 v20, s6, v23
	v_lshl_add_u64 v[18:19], v[24:25], 0, v[0:1]
	v_mul_u32_u24_e32 v0, 0x110, v23
	s_add_i32 s6, s16, s7
	v_add3_u32 v26, v0, v22, 0
	v_add_u32_e32 v22, s6, v23
	s_lshl_b32 s6, s10, 16
	s_and_b32 s6, s6, 0x3fc0000
	v_mov_b32_e32 v21, s12
	v_lshl_or_b32 v0, v23, 11, s6
	v_lshl_add_u64 v[20:21], v[20:21], 2, s[8:9]
	v_lshl_add_u64 v[24:25], v[24:25], 0, v[0:1]
	v_lshl_add_u64 v[18:19], s[64:65], 0, v[18:19]
	v_lshl_add_u64 v[20:21], v[20:21], 0, 64
	v_lshl_add_u64 v[24:25], s[64:65], 0, v[24:25]
	s_mov_b64 s[6:7], 0
